# HGRN state update: packed decay multiplies beside the MFMAs split into scalar pairs
# baseline (speedup 1.0000x reference)
; #define LAS __attribute__((address_space(3)))
; template <bool OUT>
; __device__ void phase_hgrn(const Params& p, const bf16_t* Qh, const bf16_t* Vv, const _Float16* Lfb, bf16_t* Of, bf16_t* Ob, float* Sseg, float* Dlog, LAS unsigned char* lds) {
;     ...
; #pragma unroll
;         for (int g = 0; g < 4; ++g) {
;           const f32x4 d0 = *(const LAS f32x4*)(lds + DC + (32 * (2 * wh) + 8 * g + 4 * hh) * 4);
;           const f32x4 d1 = *(const LAS f32x4*)(lds + DC + (32 * (2 * wh + 1) + 8 * g + 4 * hh) * 4);
; #pragma unroll
;           for (int j = 0; j < 4; ++j) { S0[4 * g + j] *= d0[j]; S1[4 * g + j] *= d1[j]; }
;         }
; #pragma unroll
;         for (int ks = 0; ks < 4; ++ks) {
;           const bf16x8 vb = *(const LAS bf16x8*)(lds + VT + ((32 * dvb + r) * 72 + 16 * ks + 8 * hh) * 2);
;           const bf16x8 k0 = *(const LAS bf16x8*)(lds + KE + ((32 * (2 * wh) + r) * 72 + 16 * ks + 8 * hh) * 2);
;           const bf16x8 k1 = *(const LAS bf16x8*)(lds + KE + ((32 * (2 * wh + 1) + r) * 72 + 16 * ks + 8 * hh) * 2);
;           S0 = __builtin_amdgcn_mfma_f32_32x32x16_bf16(k0, vb, S0, 0, 0, 0);
;           S1 = __builtin_amdgcn_mfma_f32_32x32x16_bf16(k1, vb, S1, 0, 0, 0);
;         }
.LBB0_2217:
	ds_read_b128 v[80:83], v56
	ds_read_b128 v[84:87], v56 offset:32
	ds_read_b128 v[88:91], v56 offset:64
	ds_read_b128 v[92:95], v56 offset:96
	ds_read_b128 v[96:99], v56 offset:128
	ds_read_b128 v[100:103], v56 offset:160
	ds_read_b128 v[104:107], v56 offset:192
	ds_read_b128 v[108:111], v56 offset:224
	v_add_u32_e32 v54, 0, v45
	s_waitcnt lgkmcnt(5)
	v_mul_f32_e32 v8, v8, v88
	v_mul_f32_e32 v9, v9, v89
	v_mul_f32_e32 v10, v10, v90
	v_mul_f32_e32 v11, v11, v91
	ds_read_b128 v[88:91], v54 offset:34816
	v_mul_f32_e32 v0, v0, v80
	v_mul_f32_e32 v1, v1, v81
	v_mul_f32_e32 v2, v2, v82
	v_mul_f32_e32 v3, v3, v83
	ds_read_b128 v[80:83], v57 offset:53248
	s_waitcnt lgkmcnt(6)
	v_mul_f32_e32 v12, v12, v92
	v_mul_f32_e32 v13, v13, v93
	v_mul_f32_e32 v4, v4, v84
	v_mul_f32_e32 v5, v5, v85
	v_mul_f32_e32 v14, v14, v94
	v_mul_f32_e32 v15, v15, v95
	v_mul_f32_e32 v6, v6, v86
	v_mul_f32_e32 v7, v7, v87
	ds_read_b128 v[84:87], v57 offset:53280
	ds_read_b128 v[92:95], v54 offset:34848
	ds_read_b128 v[112:115], v58 offset:34816
	s_waitcnt lgkmcnt(3)
	v_mfma_f32_32x32x16_bf16 v[0:15], v[88:91], v[80:83], v[0:15]
	v_mul_f32_e64 v28, v28, v108
	v_mul_f32_e64 v29, v29, v109
	v_mul_f32_e64 v24, v24, v104
	v_mul_f32_e64 v25, v25, v105
	v_mul_f32_e64 v20, v20, v100
	v_mul_f32_e64 v21, v21, v101
	v_mul_f32_e32 v16, v16, v96
	v_mul_f32_e32 v17, v17, v97
	v_mul_f32_e32 v30, v30, v110
	v_mul_f32_e32 v31, v31, v111
	v_mul_f32_e32 v26, v26, v106
	v_mul_f32_e32 v27, v27, v107
	v_mul_f32_e32 v22, v22, v102
	v_mul_f32_e32 v23, v23, v103
	v_mul_f32_e32 v18, v18, v98
	v_mul_f32_e32 v19, v19, v99
	ds_read_b128 v[88:91], v58 offset:34848
	s_waitcnt lgkmcnt(2)
	v_mfma_f32_32x32x16_bf16 v[0:15], v[92:95], v[84:87], v[0:15]
	s_add_i32 s54, s54, 64
	s_sub_i32 s3, s3, 64
	v_add_f32_e32 v60, v60, v78
	s_cmpk_eq_i32 s54, 0x840
	s_waitcnt lgkmcnt(1)
	v_mfma_f32_32x32x16_bf16 v[16:31], v[112:115], v[80:83], v[16:31]
	s_waitcnt lgkmcnt(0)
	v_mfma_f32_32x32x16_bf16 v[16:31], v[88:91], v[84:87], v[16:31]
	ds_read_b128 v[80:83], v54 offset:34880
	ds_read_b128 v[84:87], v57 offset:53312
	ds_read_b128 v[88:91], v57 offset:53344
	ds_read_b128 v[92:95], v54 offset:34912
	s_waitcnt lgkmcnt(2)
	v_mfma_f32_32x32x16_bf16 v[0:15], v[80:83], v[84:87], v[0:15]
	ds_read_b128 v[80:83], v58 offset:34880
	ds_read_b128 v[96:99], v58 offset:34912
	s_waitcnt lgkmcnt(1)
	v_mfma_f32_32x32x16_bf16 v[16:31], v[80:83], v[84:87], v[16:31]
	v_mfma_f32_32x32x16_bf16 v[0:15], v[92:95], v[88:91], v[0:15]
	s_waitcnt lgkmcnt(0)
	v_mfma_f32_32x32x16_bf16 v[16:31], v[96:99], v[88:91], v[16:31]
	s_cbranch_scc1 .LBB0_2219
	s_waitcnt vmcnt(0)
	v_lshl_or_b32 v32, v213, 16, v212
	v_lshl_or_b32 v33, v215, 16, v214
	v_lshl_or_b32 v34, v217, 16, v216
	v_lshl_or_b32 v35, v219, 16, v218
	v_lshl_or_b32 v36, v221, 16, v220
	v_lshl_or_b32 v37, v223, 16, v222
	v_lshl_or_b32 v38, v225, 16, v224
	v_lshl_or_b32 v39, v227, 16, v226
	s_mov_b32 s63, s4
	s_branch .LBB0_2209

; #define LAS __attribute__((address_space(3)))
; template <bool OUT>
; __device__ void phase_hgrn(const Params& p, const bf16_t* Qh, const bf16_t* Vv, const _Float16* Lfb, bf16_t* Of, bf16_t* Ob, float* Sseg, float* Dlog, LAS unsigned char* lds) {
;     ...
; #pragma unroll
;         for (int g = 0; g < 4; ++g) {
;           const f32x4 d0 = *(const LAS f32x4*)(lds + DC + (32 * (2 * wh) + 8 * g + 4 * hh) * 4);
;           const f32x4 d1 = *(const LAS f32x4*)(lds + DC + (32 * (2 * wh + 1) + 8 * g + 4 * hh) * 4);
; #pragma unroll
;           for (int j = 0; j < 4; ++j) { S0[4 * g + j] *= d0[j]; S1[4 * g + j] *= d1[j]; }
;         }
; #pragma unroll
;         for (int ks = 0; ks < 4; ++ks) {
;           const bf16x8 vb = *(const LAS bf16x8*)(lds + VT + ((32 * dvb + r) * 72 + 16 * ks + 8 * hh) * 2);
;           const bf16x8 k0 = *(const LAS bf16x8*)(lds + KE + ((32 * (2 * wh) + r) * 72 + 16 * ks + 8 * hh) * 2);
;           const bf16x8 k1 = *(const LAS bf16x8*)(lds + KE + ((32 * (2 * wh + 1) + r) * 72 + 16 * ks + 8 * hh) * 2);
;           S0 = __builtin_amdgcn_mfma_f32_32x32x16_bf16(k0, vb, S0, 0, 0, 0);
;           S1 = __builtin_amdgcn_mfma_f32_32x32x16_bf16(k1, vb, S1, 0, 0, 0);
;         }
;       }
;       if constexpr (OUT) {
;       __syncthreads();
;       {
;         const int tb = wh;
;         f32x16 o;
; #pragma unroll
;         for (int e = 0; e < 16; ++e) o[e] = 0.f;
; #pragma unroll
;         for (int ks = 0; ks < 4; ++ks) {
;           if (ks < 2 * (tb + 1)) {
;             const bf16x8 va = *(const LAS bf16x8*)(lds + VT + ((32 * dvb + r) * 72 + 16 * ks + 8 * hh) * 2);
;             const bf16x8 ab = *(const LAS bf16x8*)(lds + AT + ((32 * tb + r) * 72 + 16 * ks + 8 * hh) * 2);
;             o = __builtin_amdgcn_mfma_f32_32x32x16_bf16(va, ab, o, 0, 0, 0);
;           }
;         }
.LBB0_2302:
	s_or_b64 exec, exec, s[0:1]
	v_add_u32_e32 v60, 0, v82
	ds_read_b128 v[32:35], v108 offset:96
	ds_read_b128 v[36:39], v108 offset:64
	ds_read_b128 v[40:43], v108 offset:32
	ds_read_b128 v[44:47], v108
	ds_read_b128 v[56:59], v60 offset:34816
	s_waitcnt lgkmcnt(4)
	v_mul_f32_e32 v12, v12, v32
	v_mul_f32_e32 v13, v13, v33
	v_mul_f32_e32 v14, v14, v34
	v_mul_f32_e32 v15, v15, v35
	ds_read_b128 v[32:35], v113 offset:53248
	s_waitcnt lgkmcnt(4)
	v_mul_f32_e32 v8, v8, v36
	v_mul_f32_e32 v9, v9, v37
	s_waitcnt lgkmcnt(3)
	v_mul_f32_e32 v4, v4, v40
	v_mul_f32_e32 v5, v5, v41
	v_mul_f32_e32 v10, v10, v38
	v_mul_f32_e32 v11, v11, v39
	v_mul_f32_e32 v6, v6, v42
	v_mul_f32_e32 v7, v7, v43
	s_waitcnt lgkmcnt(2)
	v_mul_f32_e32 v2, v2, v46
	v_mul_f32_e32 v3, v3, v47
	v_mul_f32_e32 v0, v0, v44
	v_mul_f32_e32 v1, v1, v45
	ds_read_b128 v[36:39], v113 offset:53280
	ds_read_b128 v[40:43], v60 offset:34848
	s_waitcnt lgkmcnt(2)
	v_mfma_f32_32x32x16_bf16 v[0:15], v[56:59], v[32:35], v[0:15]
	s_waitcnt lgkmcnt(0)
	v_mfma_f32_32x32x16_bf16 v[0:15], v[40:43], v[36:39], v[0:15]
	ds_read_b128 v[40:43], v60 offset:34880
	ds_read_b128 v[44:47], v113 offset:53312
	ds_read_b128 v[56:59], v113 offset:53344
	ds_read_b128 v[60:63], v60 offset:34912
	s_waitcnt lgkmcnt(2)
	v_mfma_f32_32x32x16_bf16 v[0:15], v[40:43], v[44:47], v[0:15]
	ds_read_b128 v[40:43], v108 offset:224
	ds_read_b128 v[140:143], v108 offset:192
	ds_read_b128 v[144:147], v108 offset:128
	ds_read_b128 v[148:151], v108 offset:160
	ds_read_b128 v[152:155], v109 offset:34816
	s_waitcnt lgkmcnt(4)
	v_mul_f32_e32 v28, v28, v40
	v_mul_f32_e32 v29, v29, v41
	s_waitcnt lgkmcnt(3)
	v_mul_f32_e32 v24, v24, v140
	v_mul_f32_e32 v25, v25, v141
	v_mul_f32_e32 v30, v30, v42
	v_mul_f32_e32 v31, v31, v43
	s_waitcnt lgkmcnt(1)
	v_mul_f32_e32 v20, v20, v148
	v_mul_f32_e32 v21, v21, v149
	v_mul_f32_e32 v26, v26, v142
	v_mul_f32_e32 v27, v27, v143
	v_mul_f32_e32 v22, v22, v150
	v_mul_f32_e32 v23, v23, v151
	v_mul_f32_e32 v18, v18, v146
	v_mul_f32_e32 v19, v19, v147
	v_mul_f32_e32 v16, v16, v144
	v_mul_f32_e32 v17, v17, v145
	ds_read_b128 v[40:43], v109 offset:34848
	v_mfma_f32_32x32x16_bf16 v[0:15], v[60:63], v[56:59], v[0:15]
	v_add_u32_e32 v140, s26, v83
	s_waitcnt lgkmcnt(1)
	v_mfma_f32_32x32x16_bf16 v[16:31], v[152:155], v[32:35], v[16:31]
	ds_read_b128 v[32:35], v109 offset:34880
	ds_read_b128 v[60:63], v109 offset:34912
	s_waitcnt lgkmcnt(0)
	s_barrier
	v_mfma_f32_32x32x16_bf16 v[16:31], v[40:43], v[36:39], v[16:31]
	ds_read_b128 v[36:39], v113 offset:53248
	v_mfma_f32_32x32x16_bf16 v[16:31], v[32:35], v[44:47], v[16:31]
	v_add_u32_e32 v32, 0, v83
	v_add_u32_e32 v40, 0x11800, v32
	ds_read_b128 v[32:35], v40
	ds_read_b128 v[142:145], v113 offset:53280
	ds_read_b128 v[146:149], v40 offset:32
	s_waitcnt lgkmcnt(2)
	v_mfma_f32_32x32x16_bf16 v[32:47], v[36:39], v[32:35], 0
	s_waitcnt lgkmcnt(0)
	v_mfma_f32_32x32x16_bf16 v[32:47], v[142:145], v[146:149], v[32:47]
	s_and_saveexec_b64 s[0:1], s[10:11]
	s_cbranch_execz .LBB0_2304
	ds_read_b128 v[142:145], v113 offset:53312
	ds_read_b128 v[146:149], v140 offset:64
	s_waitcnt lgkmcnt(0)
	v_mfma_f32_32x32x16_bf16 v[32:47], v[142:145], v[146:149], v[32:47]
